# grid barrier: release word replicated per XCC (pollers of an XCD poll their own copy; last arriver of each XCD adds to all copies)
# baseline (speedup 1.0000x reference)
.LBB0_147:
	s_or_b64 exec, exec, s[14:15]
	v_cvt_f32_u32_e32 v4, v2
	s_waitcnt vmcnt(0)
	v_readfirstlane_b32 s3, v3
	v_sub_u32_e32 v3, 0, v2
	v_rcp_iflag_f32_e32 v4, v4
	v_add_u32_e32 v5, s3, v1
	v_mul_f32_e32 v4, 0x4f7ffffe, v4
	v_cvt_u32_f32_e32 v4, v4
	v_mul_lo_u32 v1, v3, v4
	v_mul_hi_u32 v1, v4, v1
	v_add_u32_e32 v1, v4, v1
	v_mul_hi_u32 v1, v5, v1
	v_mul_lo_u32 v3, v1, v2
	v_sub_u32_e32 v3, v5, v3
	v_add_u32_e32 v4, 1, v1
	v_cmp_ge_u32_e32 vcc, v3, v2
	s_nop 1
	v_cndmask_b32_e32 v1, v1, v4, vcc
	v_sub_u32_e32 v4, v3, v2
	v_cndmask_b32_e32 v3, v3, v4, vcc
	v_add_u32_e32 v4, 1, v1
	v_cmp_ge_u32_e32 vcc, v3, v2
	v_add_u32_e32 v3, 1, v5
	s_nop 0
	v_cndmask_b32_e32 v1, v1, v4, vcc
	v_mul_lo_u32 v4, v2, v1
	v_add_u32_e32 v2, v4, v2
	v_cmp_ne_u32_e32 vcc, v3, v2
	s_waitcnt lgkmcnt(0)
	s_cbranch_vccnz .Lbk0_poll
	buffer_wbl2 sc1
	s_waitcnt vmcnt(0)
	v_mov_b32_e32 v6, 0x3600
	v_mov_b32_e32 v7, 1
	global_atomic_add v6, v7, s[42:43]
	global_atomic_add v6, v7, s[42:43] offset:128
	global_atomic_add v6, v7, s[42:43] offset:256
	global_atomic_add v6, v7, s[42:43] offset:384
	global_atomic_add v6, v7, s[42:43] offset:512
	global_atomic_add v6, v7, s[42:43] offset:640
	global_atomic_add v6, v7, s[42:43] offset:768
	global_atomic_add v6, v7, s[42:43] offset:896
	global_atomic_add v6, v7, s[42:43] offset:1024
	global_atomic_add v6, v7, s[42:43] offset:1152
	global_atomic_add v6, v7, s[42:43] offset:1280
	global_atomic_add v6, v7, s[42:43] offset:1408
	global_atomic_add v6, v7, s[42:43] offset:1536
	global_atomic_add v6, v7, s[42:43] offset:1664
	global_atomic_add v6, v7, s[42:43] offset:1792
	global_atomic_add v6, v7, s[42:43] offset:1920
.Lbk0_poll:
	v_add_u32_e32 v7, 1, v1
	v_mul_lo_u32 v7, v7, v0
	v_readlane_b32 s98, v252, 0
	s_lshl_b32 s98, s98, 7
	s_add_u32 s98, s98, 0x3600
	v_mov_b32_e32 v6, s98
	s_mov_b32 s98, 0
	global_load_dword v253, v6, s[42:43] sc1

.LBB0_374:
	s_or_b64 exec, exec, s[14:15]
	v_cvt_f32_u32_e32 v4, v2
	s_waitcnt vmcnt(0)
	v_readfirstlane_b32 s3, v3
	v_sub_u32_e32 v3, 0, v2
	v_rcp_iflag_f32_e32 v4, v4
	v_add_u32_e32 v5, s3, v1
	v_mul_f32_e32 v4, 0x4f7ffffe, v4
	v_cvt_u32_f32_e32 v4, v4
	v_mul_lo_u32 v1, v3, v4
	v_mul_hi_u32 v1, v4, v1
	v_add_u32_e32 v1, v4, v1
	v_mul_hi_u32 v1, v5, v1
	v_mul_lo_u32 v3, v1, v2
	v_sub_u32_e32 v3, v5, v3
	v_add_u32_e32 v4, 1, v1
	v_cmp_ge_u32_e32 vcc, v3, v2
	s_nop 1
	v_cndmask_b32_e32 v1, v1, v4, vcc
	v_sub_u32_e32 v4, v3, v2
	v_cndmask_b32_e32 v3, v3, v4, vcc
	v_add_u32_e32 v4, 1, v1
	v_cmp_ge_u32_e32 vcc, v3, v2
	v_add_u32_e32 v3, 1, v5
	s_nop 0
	v_cndmask_b32_e32 v1, v1, v4, vcc
	v_mul_lo_u32 v4, v2, v1
	v_add_u32_e32 v2, v4, v2
	v_cmp_ne_u32_e32 vcc, v3, v2
	s_waitcnt lgkmcnt(0)
	s_cbranch_vccnz .Lbk1_poll
	v_mov_b32_e32 v6, 0x3600
	v_mov_b32_e32 v7, 1
	global_atomic_add v6, v7, s[42:43]
	global_atomic_add v6, v7, s[42:43] offset:128
	global_atomic_add v6, v7, s[42:43] offset:256
	global_atomic_add v6, v7, s[42:43] offset:384
	global_atomic_add v6, v7, s[42:43] offset:512
	global_atomic_add v6, v7, s[42:43] offset:640
	global_atomic_add v6, v7, s[42:43] offset:768
	global_atomic_add v6, v7, s[42:43] offset:896
	global_atomic_add v6, v7, s[42:43] offset:1024
	global_atomic_add v6, v7, s[42:43] offset:1152
	global_atomic_add v6, v7, s[42:43] offset:1280
	global_atomic_add v6, v7, s[42:43] offset:1408
	global_atomic_add v6, v7, s[42:43] offset:1536
	global_atomic_add v6, v7, s[42:43] offset:1664
	global_atomic_add v6, v7, s[42:43] offset:1792
	global_atomic_add v6, v7, s[42:43] offset:1920

.LBB0_1453:
	s_or_b64 exec, exec, s[12:13]
	v_cvt_f32_u32_e32 v4, v2
	s_waitcnt vmcnt(0)
	v_readfirstlane_b32 s3, v3
	v_sub_u32_e32 v3, 0, v2
	v_rcp_iflag_f32_e32 v4, v4
	v_add_u32_e32 v5, s3, v1
	v_mul_f32_e32 v4, 0x4f7ffffe, v4
	v_cvt_u32_f32_e32 v4, v4
	v_mul_lo_u32 v1, v3, v4
	v_mul_hi_u32 v1, v4, v1
	v_add_u32_e32 v1, v4, v1
	v_mul_hi_u32 v1, v5, v1
	v_mul_lo_u32 v3, v1, v2
	v_sub_u32_e32 v3, v5, v3
	v_add_u32_e32 v4, 1, v1
	v_cmp_ge_u32_e32 vcc, v3, v2
	s_nop 1
	v_cndmask_b32_e32 v1, v1, v4, vcc
	v_sub_u32_e32 v4, v3, v2
	v_cndmask_b32_e32 v3, v3, v4, vcc
	v_add_u32_e32 v4, 1, v1
	v_cmp_ge_u32_e32 vcc, v3, v2
	v_add_u32_e32 v3, 1, v5
	s_nop 0
	v_cndmask_b32_e32 v1, v1, v4, vcc
	v_mul_lo_u32 v4, v2, v1
	v_add_u32_e32 v2, v4, v2
	v_cmp_ne_u32_e32 vcc, v3, v2
	s_waitcnt lgkmcnt(0)
	s_cbranch_vccnz .Lbk11_poll
	v_mov_b32_e32 v6, 0x3600
	v_mov_b32_e32 v7, 1
	global_atomic_add v6, v7, s[42:43]
	global_atomic_add v6, v7, s[42:43] offset:128
	global_atomic_add v6, v7, s[42:43] offset:256
	global_atomic_add v6, v7, s[42:43] offset:384
	global_atomic_add v6, v7, s[42:43] offset:512
	global_atomic_add v6, v7, s[42:43] offset:640
	global_atomic_add v6, v7, s[42:43] offset:768
	global_atomic_add v6, v7, s[42:43] offset:896
	global_atomic_add v6, v7, s[42:43] offset:1024
	global_atomic_add v6, v7, s[42:43] offset:1152
	global_atomic_add v6, v7, s[42:43] offset:1280
	global_atomic_add v6, v7, s[42:43] offset:1408
	global_atomic_add v6, v7, s[42:43] offset:1536
	global_atomic_add v6, v7, s[42:43] offset:1664
	global_atomic_add v6, v7, s[42:43] offset:1792
	global_atomic_add v6, v7, s[42:43] offset:1920
